# v65 + final RMSNorm loop software-pipelined one row deep (next row loaded while the current one is normalised/stored)
# baseline (speedup 1.0000x reference)
; __device__ __forceinline__ void unpack8(u32x4 g, f32x4& a, f32x4& b) { a = (f32x4){bf_lo(g.x), bf_hi(g.x), bf_lo(g.y), bf_hi(g.y)}; b = (f32x4){bf_lo(g.z), bf_hi(g.z), bf_lo(g.w), bf_hi(g.w)}; }
; __device__ __forceinline__ void final_phase(const Args& a) {
;     int tid = threadIdx.x; asm volatile("" : "+v"(tid));
;     const int lane = tid & 63, wave = tid >> 6;
;     const int gw = blockIdx.x * 8 + wave, NGW = gridDim.x * 8;
;     const float* ssq = (const float*)(a.ws + WS_SSQ) + 2 * MTOK;
;     const bf16_t* HB = (const bf16_t*)(a.ws + WS_HB0);
;     const f32x4* fg = (const f32x4*)a.in[I_FNG] + 2 * lane;
;     for (int mrow = gw; mrow < MTOK; mrow += NGW) {
;         const float rs = __builtin_amdgcn_rsqf(ssq[mrow] * (1.0f / DM) + RMS_EPS);
;         const u32x4* hr = (const u32x4*)(HB + (size_t)mrow * DM) + lane; f32x4* orow = (f32x4*)(a.out + (size_t)mrow * DM) + 2 * lane;
;         u32x4 hv[4];
; #pragma unroll
;         for (int j = 0; j < 4; ++j) hv[j] = hr[64 * j];
;         asm volatile("" ::: "memory");
; #pragma unroll
;         for (int j = 0; j < 4; ++j) { f32x4 h0, h1; unpack8(hv[j], h0, h1); orow[128 * j] = h0 * rs * fg[128 * j]; orow[128 * j + 1] = h1 * rs * fg[128 * j + 1]; }
;     }
.LBB0_887:
	s_cmp_lt_i32 s96, 14
	s_cselect_b64 s[0:1], -1, 0
	s_cmp_gt_i32 s97, 13
	s_cselect_b64 s[4:5], -1, 0
	s_and_b64 s[0:1], s[0:1], s[4:5]
	s_and_b64 vcc, exec, s[0:1]
	s_cbranch_vccz .LBB0_891
	s_movk_i32 s0, 0x2000
	v_ashrrev_i32_e32 v0, 6, v188
	v_lshl_add_u32 v0, s2, 3, v0
	v_cmp_gt_i32_e32 vcc, s0, v0
	s_and_saveexec_b64 s[0:1], vcc
	v_readlane_b32 s8, v251, 39
	v_readlane_b32 s9, v251, 40
	v_readlane_b32 s10, v251, 41
	v_readlane_b32 s11, v251, 42
	s_cbranch_execz .LBB0_891
	v_and_b32_e32 v18, 63, v188
	v_readlane_b32 s12, v252, 20
	v_ashrrev_i32_e32 v1, 31, v0
	v_lshlrev_b32_e32 v16, 5, v18
	v_mov_b32_e32 v17, 0
	v_readlane_b32 s26, v252, 34
	v_readlane_b32 s27, v252, 35
	v_lshlrev_b64 v[14:15], 12, v[0:1]
	s_mov_b64 s[2:3], 0x1010
	s_waitcnt lgkmcnt(0)
	v_lshl_add_u64 v[2:3], s[26:27], 0, v[16:17]
	v_lshl_or_b32 v14, v18, 4, v14
	v_lshlrev_b64 v[18:19], 13, v[0:1]
	s_lshl_b32 s0, s58, 3
	v_lshl_add_u64 v[6:7], v[2:3], 0, s[2:3]
	s_mov_b64 s[2:3], 0x1800
	v_or_b32_e32 v18, v18, v16
	s_mov_b64 s[6:7], 0x1000
	v_lshl_add_u64 v[8:9], v[2:3], 0, s[2:3]
	s_mov_b64 s[2:3], 0x1810
	v_mov_b64_e32 v[12:13], 0x10000
	s_ashr_i32 s1, s0, 31
	v_lshl_add_u64 v[16:17], s[8:9], 0, v[18:19]
	v_lshl_add_u64 v[4:5], v[2:3], 0, s[6:7]
	v_lshl_add_u64 v[10:11], v[2:3], 0, s[2:3]
	v_lshl_add_u64 v[12:13], v[0:1], 2, v[12:13]
	s_lshl_b64 s[2:3], s[0:1], 2
	s_lshl_b64 s[4:5], s[0:1], 12
	v_lshl_add_u64 v[16:17], v[16:17], 0, s[6:7]
	s_lshl_b64 s[6:7], s[0:1], 13
	s_mov_b64 s[8:9], 0
	v_mov_b32_e32 v1, 0x358637bd
	s_movk_i32 s1, 0x1fff
	v_readlane_b32 s13, v252, 21
	v_readlane_b32 s14, v252, 22
	v_readlane_b32 s15, v252, 23
	v_readlane_b32 s16, v252, 24
	v_readlane_b32 s17, v252, 25
	v_readlane_b32 s18, v252, 26
	v_readlane_b32 s19, v252, 27
	v_readlane_b32 s20, v252, 28
	v_readlane_b32 s21, v252, 29
	v_readlane_b32 s22, v252, 30
	v_readlane_b32 s23, v252, 31
	v_readlane_b32 s24, v252, 32
	v_readlane_b32 s25, v252, 33
	global_load_dwordx4 v[44:47], v[2:3], off
	global_load_dwordx4 v[48:51], v[2:3], off offset:16
	global_load_dwordx4 v[52:55], v[2:3], off offset:2048
	global_load_dwordx4 v[56:59], v[2:3], off offset:2064
	global_load_dwordx4 v[60:63], v[4:5], off
	global_load_dwordx4 v[64:67], v[6:7], off
	global_load_dwordx4 v[68:71], v[8:9], off
	global_load_dwordx4 v[72:75], v[10:11], off
	v_lshl_add_u64 v[78:79], s[10:11], 0, v[12:13]
	global_load_dword v76, v[78:79], off
	v_lshl_add_u64 v[78:79], s[10:11], 0, v[14:15]
	v_add_co_u32_e32 v78, vcc, 0xfc00000, v78
	v_add_u32_e32 v0, s0, v0
	s_nop 0
	v_addc_co_u32_e32 v79, vcc, 0, v79, vcc
	global_load_dwordx4 v[80:83], v[78:79], off
	global_load_dwordx4 v[84:87], v[78:79], off offset:1024
	global_load_dwordx4 v[88:91], v[78:79], off offset:2048
	global_load_dwordx4 v[92:95], v[78:79], off offset:3072
	v_cmp_lt_i32_e32 vcc, s1, v0
	v_lshl_add_u64 v[12:13], v[12:13], 0, s[2:3]
	v_lshl_add_u64 v[14:15], v[14:15], 0, s[4:5]
	s_or_b64 s[8:9], vcc, s[8:9]
; __device__ __forceinline__ void unpack8(u32x4 g, f32x4& a, f32x4& b) { a = (f32x4){bf_lo(g.x), bf_hi(g.x), bf_lo(g.y), bf_hi(g.y)}; b = (f32x4){bf_lo(g.z), bf_hi(g.z), bf_lo(g.w), bf_hi(g.w)}; }
; __device__ __forceinline__ void final_phase(const Args& a) {
;     ...
;     for (int mrow = gw; mrow < MTOK; mrow += NGW) {
;         const float rs = __builtin_amdgcn_rsqf(ssq[mrow] * (1.0f / DM) + RMS_EPS);
;         const u32x4* hr = (const u32x4*)(HB + (size_t)mrow * DM) + lane; f32x4* orow = (f32x4*)(a.out + (size_t)mrow * DM) + 2 * lane;
;         u32x4 hv[4];
; #pragma unroll
;         for (int j = 0; j < 4; ++j) hv[j] = hr[64 * j];
;         asm volatile("" ::: "memory");
; #pragma unroll
;         for (int j = 0; j < 4; ++j) { f32x4 h0, h1; unpack8(hv[j], h0, h1); orow[128 * j] = h0 * rs * fg[128 * j]; orow[128 * j + 1] = h1 * rs * fg[128 * j + 1]; }
;     }
.LBB0_890:
	s_waitcnt vmcnt(0)
	v_mov_b32_e32 v38, v76
	v_mov_b64_e32 v[18:19], v[80:81]
	v_mov_b64_e32 v[20:21], v[82:83]
	v_mov_b64_e32 v[22:23], v[84:85]
	v_mov_b64_e32 v[24:25], v[86:87]
	v_mov_b64_e32 v[26:27], v[88:89]
	v_mov_b64_e32 v[28:29], v[90:91]
	v_mov_b64_e32 v[30:31], v[92:93]
	v_mov_b64_e32 v[32:33], v[94:95]
	v_lshl_add_u64 v[78:79], s[10:11], 0, v[12:13]
	global_load_dword v76, v[78:79], off
	v_lshl_add_u64 v[78:79], s[10:11], 0, v[14:15]
	v_add_co_u32_e32 v78, vcc, 0xfc00000, v78
	v_add_u32_e32 v0, s0, v0
	s_nop 0
	v_addc_co_u32_e32 v79, vcc, 0, v79, vcc
	global_load_dwordx4 v[80:83], v[78:79], off
	global_load_dwordx4 v[84:87], v[78:79], off offset:1024
	global_load_dwordx4 v[88:91], v[78:79], off offset:2048
	global_load_dwordx4 v[92:95], v[78:79], off offset:3072
	v_cmp_lt_i32_e32 vcc, s1, v0
	v_lshl_add_u64 v[12:13], v[12:13], 0, s[2:3]
	v_lshl_add_u64 v[14:15], v[14:15], 0, s[4:5]
	s_or_b64 s[98:99], vcc, s[8:9]
	v_fmamk_f32 v38, v38, 0x3a000000, v1
	v_rsq_f32_e32 v38, v38
	v_lshlrev_b32_e32 v40, 16, v18
	v_and_b32_e32 v41, 0xffff0000, v18
	v_lshlrev_b32_e32 v18, 16, v19
	v_and_b32_e32 v19, 0xffff0000, v19
	v_pk_mul_f32 v[40:41], v[38:39], v[40:41] op_sel_hi:[0,1]
	v_pk_mul_f32 v[18:19], v[38:39], v[18:19] op_sel_hi:[0,1]
	v_pk_mul_f32 v[36:37], v[46:47], v[18:19]
	v_pk_mul_f32 v[34:35], v[44:45], v[40:41]
	global_store_dwordx4 v[16:17], v[34:37], off offset:-4096
	v_lshlrev_b32_e32 v18, 16, v20
	v_and_b32_e32 v19, 0xffff0000, v20
	v_lshlrev_b32_e32 v20, 16, v21
	v_and_b32_e32 v21, 0xffff0000, v21
	v_pk_mul_f32 v[20:21], v[38:39], v[20:21] op_sel_hi:[0,1]
	v_pk_mul_f32 v[18:19], v[38:39], v[18:19] op_sel_hi:[0,1]
	v_pk_mul_f32 v[18:19], v[48:49], v[18:19]
	v_pk_mul_f32 v[20:21], v[50:51], v[20:21]
	global_store_dwordx4 v[16:17], v[18:21], off offset:-4080
	v_lshlrev_b32_e32 v34, 16, v22
	v_and_b32_e32 v35, 0xffff0000, v22
	v_lshlrev_b32_e32 v22, 16, v23
	v_and_b32_e32 v23, 0xffff0000, v23
	v_pk_mul_f32 v[22:23], v[38:39], v[22:23] op_sel_hi:[0,1]
	v_pk_mul_f32 v[34:35], v[38:39], v[34:35] op_sel_hi:[0,1]
	v_pk_mul_f32 v[18:19], v[34:35], v[52:53]
	v_pk_mul_f32 v[20:21], v[22:23], v[54:55]
	global_store_dwordx4 v[16:17], v[18:21], off offset:-2048
	v_lshlrev_b32_e32 v22, 16, v24
	v_and_b32_e32 v23, 0xffff0000, v24
	v_lshlrev_b32_e32 v24, 16, v25
	v_and_b32_e32 v25, 0xffff0000, v25
	v_pk_mul_f32 v[24:25], v[38:39], v[24:25] op_sel_hi:[0,1]
	v_pk_mul_f32 v[22:23], v[38:39], v[22:23] op_sel_hi:[0,1]
	v_pk_mul_f32 v[18:19], v[22:23], v[56:57]
	v_pk_mul_f32 v[20:21], v[24:25], v[58:59]
	global_store_dwordx4 v[16:17], v[18:21], off offset:-2032
	v_lshlrev_b32_e32 v22, 16, v26
	v_and_b32_e32 v23, 0xffff0000, v26
	v_lshlrev_b32_e32 v24, 16, v27
	v_and_b32_e32 v25, 0xffff0000, v27
	v_pk_mul_f32 v[24:25], v[38:39], v[24:25] op_sel_hi:[0,1]
	v_pk_mul_f32 v[22:23], v[38:39], v[22:23] op_sel_hi:[0,1]
	v_pk_mul_f32 v[18:19], v[22:23], v[60:61]
	v_pk_mul_f32 v[20:21], v[24:25], v[62:63]
	global_store_dwordx4 v[16:17], v[18:21], off
	v_lshlrev_b32_e32 v22, 16, v28
	v_and_b32_e32 v23, 0xffff0000, v28
	v_lshlrev_b32_e32 v24, 16, v29
	v_and_b32_e32 v25, 0xffff0000, v29
	v_pk_mul_f32 v[24:25], v[38:39], v[24:25] op_sel_hi:[0,1]
	v_pk_mul_f32 v[22:23], v[38:39], v[22:23] op_sel_hi:[0,1]
	v_pk_mul_f32 v[18:19], v[22:23], v[64:65]
	v_pk_mul_f32 v[20:21], v[24:25], v[66:67]
	global_store_dwordx4 v[16:17], v[18:21], off offset:16
	v_lshlrev_b32_e32 v22, 16, v30
	v_and_b32_e32 v23, 0xffff0000, v30
	v_lshlrev_b32_e32 v24, 16, v31
	v_and_b32_e32 v25, 0xffff0000, v31
	v_pk_mul_f32 v[24:25], v[38:39], v[24:25] op_sel_hi:[0,1]
	v_pk_mul_f32 v[22:23], v[38:39], v[22:23] op_sel_hi:[0,1]
	v_pk_mul_f32 v[18:19], v[22:23], v[68:69]
	v_pk_mul_f32 v[20:21], v[24:25], v[70:71]
	global_store_dwordx4 v[16:17], v[18:21], off offset:2048
	v_lshlrev_b32_e32 v22, 16, v32
	v_and_b32_e32 v23, 0xffff0000, v32
	v_lshlrev_b32_e32 v24, 16, v33
	v_and_b32_e32 v25, 0xffff0000, v33
	v_pk_mul_f32 v[24:25], v[38:39], v[24:25] op_sel_hi:[0,1]
	v_pk_mul_f32 v[22:23], v[38:39], v[22:23] op_sel_hi:[0,1]
	v_pk_mul_f32 v[18:19], v[22:23], v[72:73]
	v_pk_mul_f32 v[20:21], v[24:25], v[74:75]
	global_store_dwordx4 v[16:17], v[18:21], off offset:2064
	v_lshl_add_u64 v[16:17], v[16:17], 0, s[6:7]
	s_andn2_b64 exec, exec, s[8:9]
	s_mov_b64 s[8:9], s[98:99]
	s_cbranch_execnz .LBB0_890
